# conv phase work decomposition: 93 time chunks (one of 12 blocks, 92 of 11) so every wave of the grid owns a chunk-task instead of 86 chunks leaving 7.6% of the waves idle
# baseline (speedup 1.0000x reference)
.Lser_exit:
	s_nop 0
	s_nop 0
	s_nop 0
	s_nop 0
	v_lshlrev_b32_e32 v157, 2, v0

.LBB0_1005:
	s_cmp_lt_i32 s34, 11
	s_cselect_b64 s[10:11], -1, 0
	s_and_b64 s[6:7], s[10:11], s[6:7]
	s_andn2_b64 vcc, exec, s[6:7]
	s_cbranch_vccnz .LBB0_1012
	v_lshl_or_b32 v1, s2, 9, v0
	s_waitcnt lgkmcnt(0)
	s_mov_b32 s3, 0x160000
	v_cmp_gt_i32_e32 vcc, s3, v1
	s_and_saveexec_b64 s[12:13], vcc
	s_cbranch_execz .LBB0_1011
	s_load_dword s3, s[0:1], 0xd8
	s_add_u32 s14, s70, 0x7900000
	s_addc_u32 s15, s71, 0
	s_add_u32 s16, s14, 0x2c00
	s_addc_u32 s17, s15, 0
	s_add_u32 s18, s70, 0x1600000
	s_addc_u32 s19, s71, 0
	s_mov_b32 s38, 0x2e8ba2e9
	v_mov_b32_e32 v216, 0
	v_mov_b32_e32 v217, 0
	v_mov_b32_e32 v110, v1
	s_waitcnt lgkmcnt(0)
	s_lshl_b32 s3, s3, 9
	s_mov_b32 s39, 0x1ff80
	v_cmp_gt_u32_e32 vcc, s39, v110
	s_and_b64 exec, exec, vcc
	s_cbranch_execz .Lcv_done
.Lcv_task:
	v_mul_hi_u32 v2, v110, s38
	v_lshrrev_b32_e32 v2, 8, v2
	v_mul_u32_u24_e32 v3, 0x580, v2
	v_sub_u32_e32 v3, v110, v3
	v_lshlrev_b32_e32 v113, 3, v3
	v_mul_u32_u24_e32 v112, 11, v2
	v_min_u32_e32 v4, 1, v2
	v_add_u32_e32 v111, v112, v4
	v_add_u32_e32 v112, 12, v112
	v_min_u32_e32 v112, 0x400, v112
	v_lshlrev_b32_e32 v4, 4, v3
	v_add_u32_e32 v5, 0xb000, v4
	global_load_dwordx4 v[72:75], v5, s[54:55]
	global_load_dwordx4 v[76:79], v4, s[54:55]
	v_add_u32_e32 v5, 0x16000, v4
	global_load_dwordx4 v[80:83], v5, s[54:55]
	global_load_dwordx4 v[84:87], v4, s[56:57]
	v_add_u32_e32 v5, 0x10800, v4
	global_load_dwordx4 v[88:91], v5, s[54:55]
	v_add_u32_e32 v5, 0x5800, v4
	global_load_dwordx4 v[92:95], v5, s[54:55]
	v_add_u32_e32 v5, 0x1b800, v4
	global_load_dwordx4 v[96:99], v5, s[54:55]
	v_add_u32_e32 v5, 0x5800, v4
	global_load_dwordx4 v[100:103], v5, s[56:57]
	v_lshlrev_b32_e32 v5, 3, v111
	v_mul_u32_u24_e32 v6, 0x5800, v5
	v_add_u32_e32 v6, v6, v113
	v_mul_u32_u24_e32 v7, 0x2c00, v5
	v_add_u32_e32 v7, v7, v113
	v_and_b32_e32 v5, 0x1ff, v111
	v_cmp_eq_u32_e32 vcc, 0, v5
	s_nop 1
	v_add_u32_e32 v4, 0xffff5000, v6
	v_cndmask_b32_e32 v4, v4, v6, vcc
	global_load_dwordx2 v[52:53], v4, s[14:15]
	global_load_dwordx2 v[68:69], v4, s[16:17]
	v_add_u32_e32 v4, 0xffffa800, v6
	v_cndmask_b32_e32 v4, v4, v6, vcc
	global_load_dwordx2 v[54:55], v4, s[14:15]
	global_load_dwordx2 v[70:71], v4, s[16:17]
	v_lshlrev_b32_e32 v5, 3, v111
	v_mul_u32_u24_e32 v6, 0x5800, v5
	v_add_u32_e32 v6, v6, v113
	v_mul_u32_u24_e32 v7, 0x2c00, v5
	v_add_u32_e32 v7, v7, v113
	v_mov_b32_e32 v117, v7
	global_load_dwordx2 v[8:9], v6, s[14:15]
	global_load_dwordx2 v[24:25], v6, s[16:17]
	v_add_u32_e32 v6, 0x5800, v6
	global_load_dwordx2 v[10:11], v6, s[14:15]
	global_load_dwordx2 v[26:27], v6, s[16:17]
	v_add_u32_e32 v6, 0x5800, v6
	global_load_dwordx2 v[12:13], v6, s[14:15]
	global_load_dwordx2 v[28:29], v6, s[16:17]
	v_add_u32_e32 v6, 0x5800, v6
	global_load_dwordx2 v[14:15], v6, s[14:15]
	global_load_dwordx2 v[30:31], v6, s[16:17]
	v_add_u32_e32 v6, 0x5800, v6
	global_load_dwordx2 v[16:17], v6, s[14:15]
	global_load_dwordx2 v[32:33], v6, s[16:17]
	v_add_u32_e32 v6, 0x5800, v6
	global_load_dwordx2 v[18:19], v6, s[14:15]
	global_load_dwordx2 v[34:35], v6, s[16:17]
	v_add_u32_e32 v6, 0x5800, v6
	global_load_dwordx2 v[20:21], v6, s[14:15]
	global_load_dwordx2 v[36:37], v6, s[16:17]
	v_add_u32_e32 v6, 0x5800, v6
	global_load_dwordx2 v[22:23], v6, s[14:15]
	global_load_dwordx2 v[38:39], v6, s[16:17]
	v_mov_b32_e32 v4, v117
	global_store_dwordx2 v4, v[216:217], s[18:19]
	v_add_u32_e32 v4, 0x2c00, v4
	global_store_dwordx2 v4, v[216:217], s[18:19]
	v_add_u32_e32 v4, 0x2c00, v4
	global_store_dwordx2 v4, v[216:217], s[18:19]
	v_add_u32_e32 v4, 0x2c00, v4
	global_store_dwordx2 v4, v[216:217], s[18:19]
	v_add_u32_e32 v4, 0x2c00, v4
	global_store_dwordx2 v4, v[216:217], s[18:19]
	v_add_u32_e32 v4, 0x2c00, v4
	global_store_dwordx2 v4, v[216:217], s[18:19]
	v_add_u32_e32 v4, 0x2c00, v4
	global_store_dwordx2 v4, v[216:217], s[18:19]
	v_add_u32_e32 v4, 0x2c00, v4
	global_store_dwordx2 v4, v[216:217], s[18:19]
	s_waitcnt vmcnt(24)
	s_mov_b64 s[6:7], exec

.Lcv_next:
	s_mov_b64 exec, s[6:7]
	v_add_u32_e32 v110, s3, v110
	s_mov_b32 s39, 0x1ff80
	v_cmp_gt_u32_e32 vcc, s39, v110
	s_and_b64 exec, exec, vcc
	s_cbranch_execnz .Lcv_task
.Lcv_done:
	s_nop 0
	s_nop 0
	s_nop 0
	s_nop 0
	s_nop 0
	s_nop 0
	s_nop 0
	s_nop 0
	s_nop 0
	s_nop 0
	s_nop 0
	s_nop 0
	s_nop 0
	s_nop 0
